# phase-3 loop first half: first mask-word wait and its dependent bit ops sunk below the QK^T ds_read/MFMA section
# baseline (speedup 1.0000x reference)
; #define MFMA16(a, b, c) __builtin_amdgcn_mfma_f32_16x16x32_f16((a), (b), (c), 0, 0, 0)
; DI void qk_tile2(f32x4 (&sa)[4], f32x4 (&sb)[4], const char* sK, const bf16x8 (&qa)[2], const bf16x8 (&qb)[2], int lr, int g) {
; #pragma unroll
;   for (int kt = 0; kt < 4; ++kt) {
;     const bf16x8 k0 = *(const bf16x8*)(sK + (kt * 16 + lr) * 128 + ((g ^ ((lr >> 1) & 7)) << 4)), k1 = *(const bf16x8*)(sK + (kt * 16 + lr) * 128 + (((4 + g) ^ ((lr >> 1) & 7)) << 4));
;     sa[kt] = MFMA16(k0, qa[0], ((f32x4){0.f, 0.f, 0.f, 0.f})); sb[kt] = MFMA16(k0, qb[0], ((f32x4){0.f, 0.f, 0.f, 0.f}));
;     sa[kt] = MFMA16(k1, qa[1], sa[kt]); sb[kt] = MFMA16(k1, qb[1], sb[kt]);
;   }
; }
.LBB0_1079:
	v_readlane_b32 s16, v254, 55
	s_add_i32 s1, s15, -2
	v_readlane_b32 s18, v254, 57
	v_readlane_b32 s19, v254, 58
	v_cmp_le_i32_e32 vcc, s1, v107
	v_readlane_b32 s17, v254, 56
	v_lshl_add_u64 v[122:123], s[18:19], 0, v[112:113]
	s_and_saveexec_b64 s[12:13], vcc
	s_cbranch_execz .LBB0_1081
	v_add_co_u32_e32 v80, vcc, 0x1b900000, v122
	s_mov_b32 s16, 0xff800000
	s_nop 0
	v_addc_co_u32_e32 v81, vcc, 0, v123, vcc
	global_load_dwordx2 v[126:127], v[80:81], off
	v_add_co_u32_e32 v80, vcc, 0x1b902000, v122
	s_nop 1
	v_addc_co_u32_e32 v81, vcc, 0, v123, vcc
	global_load_dwordx2 v[128:129], v[80:81], off
	ds_read_b128 v[80:83], v139
	ds_read_b128 v[84:87], v140
	s_waitcnt lgkmcnt(1)
	v_mfma_f32_16x16x32_f16 v[88:91], v[80:83], v[0:3], 0
	v_mfma_f32_16x16x32_f16 v[80:83], v[80:83], v[4:7], 0
	s_waitcnt lgkmcnt(0)
	v_mfma_f32_16x16x32_f16 v[142:145], v[84:87], v[8:11], v[88:91]
	v_mfma_f32_16x16x32_f16 v[154:157], v[84:87], v[12:15], v[80:83]
	s_nop 3
	s_nop 0
	ds_read_b128 v[80:83], v139 offset:2048
	ds_read_b128 v[84:87], v140 offset:2048
	s_waitcnt lgkmcnt(1)
	v_mfma_f32_16x16x32_f16 v[88:91], v[80:83], v[0:3], 0
	v_mfma_f32_16x16x32_f16 v[80:83], v[80:83], v[4:7], 0
	s_waitcnt lgkmcnt(0)
	v_mfma_f32_16x16x32_f16 v[100:103], v[84:87], v[8:11], v[88:91]
	v_mfma_f32_16x16x32_f16 v[96:99], v[84:87], v[12:15], v[80:83]
	s_nop 4
	ds_read_b128 v[80:83], v139 offset:4096
	ds_read_b128 v[88:91], v140 offset:4096
	s_waitcnt lgkmcnt(1)
	v_mfma_f32_16x16x32_f16 v[84:87], v[80:83], v[0:3], 0
	v_mfma_f32_16x16x32_f16 v[80:83], v[80:83], v[4:7], 0
	s_waitcnt lgkmcnt(0)
	v_mfma_f32_16x16x32_f16 v[84:87], v[88:91], v[8:11], v[84:87]
	v_mfma_f32_16x16x32_f16 v[80:83], v[88:91], v[12:15], v[80:83]
	ds_read_b128 v[88:91], v139 offset:6144
	ds_read_b128 v[92:95], v140 offset:6144
	s_waitcnt lgkmcnt(1)
	v_mfma_f32_16x16x32_f16 v[158:161], v[88:91], v[0:3], 0
	v_mfma_f32_16x16x32_f16 v[162:165], v[88:91], v[4:7], 0
	s_waitcnt lgkmcnt(0)
	v_mfma_f32_16x16x32_f16 v[88:91], v[92:95], v[8:11], v[158:161]
	s_waitcnt vmcnt(0)
	v_lshrrev_b32_e32 v147, v132, v126
	v_and_b32_e32 v130, 1, v147
	v_cmp_eq_u32_e32 vcc, 1, v130
	v_bfe_i32 v141, v147, 1, 1
	v_lshrrev_b32_e32 v126, v138, v126
	s_nop 4
	v_cndmask_b32_e32 v159, v187, v142, vcc
	v_bfe_i32 v142, v147, 2, 1
	v_mfma_f32_16x16x32_f16 v[92:95], v[92:95], v[12:15], v[162:165]
	s_waitcnt vmcnt(0)
	v_lshrrev_b32_e32 v158, v132, v128
	v_and_b32_e32 v130, 1, v158
	v_cmp_eq_u32_e32 vcc, 1, v130
	v_lshrrev_b32_e32 v128, v138, v128
	s_nop 0
	v_cndmask_b32_e32 v130, v187, v154, vcc
	v_bfi_b32 v154, v141, v143, v187
	v_and_b32_e32 v141, 2, v158
	v_cmp_ne_u32_e32 vcc, 0, v141
	v_bfe_i32 v143, v147, 3, 1
	v_bfe_i32 v147, v126, 0, 1
	v_cndmask_b32_e32 v141, v187, v155, vcc
	v_bfi_b32 v144, v142, v144, v187
	v_and_b32_e32 v142, 4, v158
	v_cmp_ne_u32_e32 vcc, 0, v142
	s_nop 1
	v_cndmask_b32_e32 v142, v187, v156, vcc
	v_bfi_b32 v145, v143, v145, v187
	v_and_b32_e32 v143, 8, v158
	v_cmp_ne_u32_e32 vcc, 0, v143
	s_nop 1
	v_cndmask_b32_e32 v143, v187, v157, vcc
	v_bfi_b32 v100, v147, v100, v187
	v_and_b32_e32 v147, 1, v128
	v_cmp_eq_u32_e32 vcc, 1, v147
	s_nop 1
	v_cndmask_b32_e32 v147, v187, v96, vcc
	v_and_b32_e32 v96, 2, v126
	v_cmp_ne_u32_e32 vcc, 0, v96
	s_nop 1
	v_cndmask_b32_e32 v96, v187, v101, vcc
	v_bfe_i32 v101, v128, 1, 1
	v_bfi_b32 v97, v101, v97, v187
	v_and_b32_e32 v101, 4, v126
	v_cmp_ne_u32_e32 vcc, 0, v101
	s_nop 1
	v_cndmask_b32_e32 v101, v187, v102, vcc
	v_bfe_i32 v102, v128, 2, 1
	v_bfi_b32 v98, v102, v98, v187
	v_and_b32_e32 v102, 8, v126
	v_lshrrev_b32_e32 v126, v132, v129
	v_cmp_ne_u32_e32 vcc, 0, v102
	s_nop 1
	v_cndmask_b32_e32 v102, v187, v103, vcc
	v_and_b32_e32 v103, 8, v128
	v_cmp_ne_u32_e32 vcc, 0, v103
	s_nop 1
	v_cndmask_b32_e32 v103, v187, v99, vcc
	v_lshrrev_b32_e32 v99, v132, v127
	v_bfe_i32 v128, v99, 0, 1
	v_bfi_b32 v84, v128, v84, v187
	v_and_b32_e32 v128, 1, v126
	v_cmp_eq_u32_e32 vcc, 1, v128
	s_nop 1
	v_cndmask_b32_e32 v128, v187, v80, vcc
	v_and_b32_e32 v80, 2, v99
	v_cmp_ne_u32_e32 vcc, 0, v80
	s_nop 1
	v_cndmask_b32_e32 v80, v187, v85, vcc
	v_bfe_i32 v85, v126, 1, 1
	v_bfi_b32 v81, v85, v81, v187
	v_and_b32_e32 v85, 4, v99
	v_cmp_ne_u32_e32 vcc, 0, v85
	s_nop 1
	v_cndmask_b32_e32 v85, v187, v86, vcc
	v_bfe_i32 v86, v126, 2, 1
	v_bfi_b32 v155, v86, v82, v187
	v_bfe_i32 v86, v126, 3, 1
	v_and_b32_e32 v82, 8, v99
	v_cmp_ne_u32_e32 vcc, 0, v82
	s_nop 1
	v_cndmask_b32_e32 v82, v187, v87, vcc
	v_bfi_b32 v83, v86, v83, v187
	v_lshrrev_b32_e32 v86, v138, v127
	v_lshrrev_b32_e32 v87, v138, v129
	v_bfe_i32 v99, v86, 0, 1
	v_bfi_b32 v88, v99, v88, v187
	v_bfe_i32 v99, v87, 0, 1
	v_bfi_b32 v126, v99, v92, v187
	v_bfe_i32 v92, v86, 1, 1
	v_bfi_b32 v89, v92, v89, v187
	v_bfe_i32 v92, v87, 1, 1
	v_bfi_b32 v127, v92, v93, v187
	v_bfe_i32 v92, v86, 2, 1
	v_bfe_i32 v86, v86, 3, 1
	v_bfi_b32 v93, v92, v90, v187
	v_bfe_i32 v90, v87, 2, 1
	v_bfi_b32 v129, v90, v94, v187
	v_bfi_b32 v91, v86, v91, v187
	v_bfe_i32 v86, v87, 3, 1
	v_bfi_b32 v156, v86, v95, v187
	v_max_f32_e32 v86, v144, v145
	v_max_f32_e32 v87, v101, v102
	v_max_f32_e32 v90, v84, v80
	v_max_f32_e32 v92, v85, v82
	v_max_f32_e32 v94, v93, v91
	v_max3_f32 v94, v88, v89, v94
	v_max3_f32 v86, v159, v154, v86
	v_max3_f32 v87, v100, v96, v87
	v_max3_f32 v90, v90, v92, v94
	v_max3_f32 v86, v86, v87, v90
	v_mov_b32_e32 v87, v86
	s_waitcnt lgkmcnt(0)
	s_nop 1
	v_permlane16_swap_b32_e32 v86, v87
	v_max_f32_e32 v86, v86, v87
	v_mov_b32_e32 v87, v86
	s_waitcnt lgkmcnt(0)
; DI float softmax_step(f32x4 (&st)[4], float& m, float& lsum) {
;   float mx = fmaxf(fmaxf(fmaxf(st[0][0], st[0][1]), fmaxf(st[0][2], st[0][3])), fmaxf(fmaxf(st[1][0], st[1][1]), fmaxf(st[1][2], st[1][3])));
;   mx = fmaxf(mx, fmaxf(fmaxf(fmaxf(st[2][0], st[2][1]), fmaxf(st[2][2], st[2][3])), fmaxf(fmaxf(st[3][0], st[3][1]), fmaxf(st[3][2], st[3][3]))));
;   mx = fmaxf(mx, __shfl_xor(mx, 16)); mx = fmaxf(mx, __shfl_xor(mx, 32));
;   const float mn = fmaxf(m, mx);
;   const float mu = mn == -INFINITY ? 0.f : mn;
;   const float alpha = __builtin_amdgcn_exp2f(m - mu);
;   float ps = 0.f;
; #pragma unroll
;   for (int kt = 0; kt < 4; ++kt)
; #pragma unroll
;     for (int j = 0; j < 4; ++j) { const float p = __builtin_amdgcn_exp2f(st[kt][j] - mu); st[kt][j] = p; ps += p; }
;   lsum = lsum * alpha + ps; m = mn;
;   return alpha;
	s_nop 1
	v_permlane32_swap_b32_e32 v86, v87
	v_max3_f32 v99, v131, v86, v87
	v_cmp_neq_f32_e32 vcc, s16, v99
	s_nop 1
	v_cndmask_b32_e32 v87, 0, v99, vcc
	v_sub_f32_e32 v86, v159, v87
	v_exp_f32_e32 v162, v86
	v_sub_f32_e32 v86, v154, v87
	v_exp_f32_e32 v164, v86
	v_sub_f32_e32 v86, v144, v87
	v_exp_f32_e32 v166, v86
	v_sub_f32_e32 v86, v145, v87
	v_sub_f32_e32 v80, v80, v87
	v_exp_f32_e32 v168, v86
	v_sub_f32_e32 v86, v100, v87
	v_exp_f32_e32 v94, v80
	v_sub_f32_e32 v80, v85, v87
	v_exp_f32_e32 v170, v86
	v_sub_f32_e32 v86, v96, v87
	v_exp_f32_e32 v92, v80
	v_sub_f32_e32 v80, v82, v87
	v_exp_f32_e32 v190, v86
	v_sub_f32_e32 v86, v101, v87
	v_exp_f32_e32 v90, v80
	v_sub_f32_e32 v80, v88, v87
	v_exp_f32_e32 v192, v86
	v_sub_f32_e32 v86, v102, v87
	v_exp_f32_e32 v88, v80
	v_sub_f32_e32 v80, v89, v87
	v_exp_f32_e32 v194, v86
	v_sub_f32_e32 v84, v84, v87
	v_exp_f32_e32 v86, v80
	v_sub_f32_e32 v80, v93, v87
	v_exp_f32_e32 v96, v84
	v_exp_f32_e32 v82, v80
	v_sub_f32_e32 v80, v91, v87
	v_sub_f32_e32 v84, v131, v87
	v_max_f32_e32 v85, v142, v143
	v_max_f32_e32 v87, v98, v103
	v_max_f32_e32 v89, v128, v81
	v_max_f32_e32 v91, v155, v83
	v_max_f32_e32 v93, v129, v156
	v_max3_f32 v93, v126, v127, v93
	v_max3_f32 v85, v130, v141, v85
	v_max3_f32 v87, v147, v97, v87
	v_max3_f32 v89, v89, v91, v93
	v_max3_f32 v85, v85, v87, v89
	v_mov_b32_e32 v87, v85
	v_exp_f32_e32 v84, v84
	v_exp_f32_e32 v80, v80
	v_mov_b32_e32 v131, v99
	s_waitcnt lgkmcnt(0)
	s_nop 1
	v_permlane16_swap_b32_e32 v85, v87
	v_max_f32_e32 v85, v85, v87
	v_mov_b32_e32 v87, v85
	s_waitcnt lgkmcnt(0)
	s_nop 1
	v_permlane32_swap_b32_e32 v85, v87
	v_max3_f32 v102, v146, v85, v87
	v_cmp_neq_f32_e32 vcc, s16, v102
	s_nop 1
	v_cndmask_b32_e32 v85, 0, v102, vcc
	v_sub_f32_e32 v87, v130, v85
	v_exp_f32_e32 v163, v87
	v_sub_f32_e32 v87, v141, v85
	v_exp_f32_e32 v165, v87
	v_sub_f32_e32 v87, v142, v85
	v_exp_f32_e32 v167, v87
	v_sub_f32_e32 v87, v143, v85
	v_exp_f32_e32 v169, v87
	v_sub_f32_e32 v87, v147, v85
	v_sub_f32_e32 v81, v81, v85
	v_exp_f32_e32 v171, v87
	v_sub_f32_e32 v87, v97, v85
	v_exp_f32_e32 v95, v81
	v_sub_f32_e32 v81, v155, v85
	v_exp_f32_e32 v191, v87
	v_sub_f32_e32 v87, v98, v85
	v_exp_f32_e32 v93, v81
	v_sub_f32_e32 v81, v83, v85
	v_exp_f32_e32 v193, v87
	v_sub_f32_e32 v87, v103, v85
	v_exp_f32_e32 v91, v81
	v_sub_f32_e32 v81, v126, v85
	v_exp_f32_e32 v195, v87
	v_sub_f32_e32 v87, v128, v85
	v_exp_f32_e32 v89, v81
	v_sub_f32_e32 v81, v127, v85
	v_exp_f32_e32 v97, v87
	v_exp_f32_e32 v87, v81
	v_sub_f32_e32 v81, v129, v85
	v_exp_f32_e32 v83, v81
	v_sub_f32_e32 v81, v156, v85
	v_sub_f32_e32 v85, v146, v85
	v_exp_f32_e32 v98, v85
	v_pk_mul_f32 v[156:157], v[70:71], v[84:85] op_sel_hi:[1,0]
	v_pk_mul_f32 v[154:155], v[68:69], v[84:85] op_sel_hi:[1,0]
	v_pk_mul_f32 v[128:129], v[62:63], v[84:85] op_sel_hi:[1,0]
	v_pk_mul_f32 v[142:143], v[56:57], v[98:99] op_sel_hi:[1,0]
	v_pk_mul_f32 v[70:71], v[50:51], v[98:99] op_sel_hi:[1,0]
	v_pk_mul_f32 v[68:69], v[48:49], v[98:99] op_sel_hi:[1,0]
	v_pk_mul_f32 v[50:51], v[74:75], v[84:85] op_sel_hi:[1,0]
	v_pk_mul_f32 v[48:49], v[72:73], v[84:85] op_sel_hi:[1,0]
	v_pk_add_f32 v[56:57], v[162:163], 0 op_sel_hi:[1,0]
	ds_read_b128 v[72:75], v139 offset:9216
	v_pk_add_f32 v[56:57], v[164:165], v[56:57]
	v_pk_mul_f32 v[126:127], v[60:61], v[84:85] op_sel_hi:[1,0]
	v_pk_add_f32 v[56:57], v[166:167], v[56:57]
	v_pk_mul_f32 v[144:145], v[58:59], v[98:99] op_sel_hi:[1,0]
	v_pk_add_f32 v[56:57], v[168:169], v[56:57]
	v_cvt_pk_f16_f32 v58, v170, v190
	v_pk_add_f32 v[56:57], v[170:171], v[56:57]
	v_cvt_pk_f16_f32 v59, v192, v194
	v_pk_add_f32 v[56:57], v[190:191], v[56:57]
	v_pk_mul_f32 v[160:161], v[66:67], v[98:99] op_sel_hi:[1,0]
	v_pk_add_f32 v[56:57], v[192:193], v[56:57]
	v_pk_mul_f32 v[158:159], v[64:65], v[98:99] op_sel_hi:[1,0]
	v_pk_add_f32 v[56:57], v[194:195], v[56:57]
	v_pk_mul_f32 v[66:67], v[54:55], v[84:85] op_sel_hi:[1,0]
	v_pk_add_f32 v[100:101], v[96:97], v[56:57]
	v_cvt_pk_f16_f32 v56, v162, v164
	v_cvt_pk_f16_f32 v57, v166, v168
	v_pk_mul_f32 v[64:65], v[52:53], v[84:85] op_sel_hi:[1,0]
	v_pk_mul_f32 v[54:55], v[78:79], v[98:99] op_sel_hi:[1,0]
	v_pk_mul_f32 v[52:53], v[76:77], v[98:99] op_sel_hi:[1,0]
	s_waitcnt lgkmcnt(0)
	v_mfma_f32_16x16x32_f16 v[76:79], v[72:75], v[56:59], v[126:129]
	v_cvt_pk_f16_f32 v60, v163, v165
	v_cvt_pk_f16_f32 v61, v167, v169
	v_cvt_pk_f16_f32 v62, v171, v191
	ds_read_b128 v[126:129], v139 offset:11264
	v_cvt_pk_f16_f32 v63, v193, v195
	v_exp_f32_e32 v81, v81
	v_cvt_pk_f16_f32 v190, v96, v94
	v_mfma_f32_16x16x32_f16 v[72:75], v[72:75], v[60:63], v[142:145]
	v_cvt_pk_f16_f32 v191, v92, v90
	v_cvt_pk_f16_f32 v192, v88, v86
	v_cvt_pk_f16_f32 v193, v82, v80
	s_waitcnt lgkmcnt(0)
	v_mfma_f32_16x16x32_f16 v[142:145], v[126:129], v[56:59], v[154:157]
	v_cvt_pk_f16_f32 v194, v97, v95
	v_cvt_pk_f16_f32 v195, v93, v91
	s_nop 0
	ds_read_b128 v[154:157], v139 offset:13312
	v_mfma_f32_16x16x32_f16 v[126:129], v[126:129], v[60:63], v[158:161]
	v_cvt_pk_f16_f32 v196, v89, v87
	v_cvt_pk_f16_f32 v197, v83, v81
	v_pk_add_f32 v[94:95], v[94:95], v[100:101]
	s_waitcnt lgkmcnt(0)
	v_mfma_f32_16x16x32_f16 v[158:161], v[154:157], v[56:59], v[64:67]
	s_nop 2
	ds_read_b128 v[64:67], v139 offset:15360
	v_pk_add_f32 v[92:93], v[92:93], v[94:95]
	v_mov_b32_e32 v85, v98
	s_waitcnt lgkmcnt(0)
	v_mfma_f32_16x16x32_f16 v[162:165], v[64:67], v[56:59], v[48:51]
	s_nop 2
	ds_read_b128 v[48:51], v140 offset:9216
	v_pk_add_f32 v[90:91], v[90:91], v[92:93]
	v_mov_b32_e32 v146, v102
	v_mfma_f32_16x16x32_f16 v[154:157], v[154:157], v[60:63], v[68:71]
	v_add_f32_e64 v88, v88, v90
	v_add_f32_e64 v89, v89, v91
	v_pk_add_f32 v[86:87], v[86:87], v[88:89]
	v_mfma_f32_16x16x32_f16 v[166:169], v[64:67], v[60:63], v[52:55]
	v_add_f32_e64 v82, v82, v86
	v_add_f32_e64 v83, v83, v87
	v_pk_add_f32 v[80:81], v[80:81], v[82:83]
	s_waitcnt lgkmcnt(0)
	v_mfma_f32_16x16x32_f16 v[60:63], v[48:51], v[190:193], v[76:79]
	v_fma_f32 v118, v118, v84, v80
	v_fma_f32 v119, v119, v85, v81
	v_mfma_f32_16x16x32_f16 v[56:59], v[48:51], v[194:197], v[72:75]
	ds_read_b128 v[48:51], v140 offset:11264
	ds_read_b128 v[76:79], v140 offset:15360
	s_waitcnt lgkmcnt(1)
	v_mfma_f32_16x16x32_f16 v[68:71], v[48:51], v[190:193], v[142:145]
	v_mfma_f32_16x16x32_f16 v[64:67], v[48:51], v[194:197], v[126:129]
	ds_read_b128 v[48:51], v140 offset:13312
	s_waitcnt lgkmcnt(0)
	v_mfma_f32_16x16x32_f16 v[52:55], v[48:51], v[190:193], v[158:161]
	v_mfma_f32_16x16x32_f16 v[48:51], v[48:51], v[194:197], v[154:157]
	v_mfma_f32_16x16x32_f16 v[72:75], v[76:79], v[190:193], v[162:165]
	v_mfma_f32_16x16x32_f16 v[76:79], v[76:79], v[194:197], v[166:169]
